# EpiUp GEMM epilogues de-serialised: G/MRG tiles loaded 7 (first=0) or 14 (first=1) units ahead into dead fragment VGPRs with counted vmcnt
# speedup vs baseline: 1.0061x; 1.0061x over previous
.LBB0_130:
	v_lshl_add_u32 v150, s41, 8, v144
	v_lshl_add_u32 v151, s40, 8, v146
	v_lshlrev_b32_e32 v150, 10, v150
	v_add_lshl_u32 v138, v150, v151, 1
	v_add_u32_e32 v139, 0x8000, v138
	v_add_u32_e32 v140, 0x10000, v138
	v_add_u32_e32 v141, 0x18000, v138
	v_add_u32_e32 v142, 0x40000, v138
	v_add_u32_e32 v143, 0x48000, v138
	v_add_u32_e32 v148, 0x50000, v138
	v_add_u32_e32 v149, 0x58000, v138
	s_andn2_b64 vcc, exec, s[8:9]
	s_waitcnt lgkmcnt(0)
	global_load_dwordx4 v[166:169], v138, s[12:13]
	global_load_dwordx4 v[170:173], v138, s[12:13] offset:256
	global_load_dwordx4 v[174:177], v139, s[12:13]
	global_load_dwordx4 v[178:181], v139, s[12:13] offset:256
	global_load_dwordx4 v[182:185], v140, s[12:13]
	global_load_dwordx4 v[186:189], v140, s[12:13] offset:256
	global_load_dwordx4 v[190:193], v141, s[12:13]
	global_load_dwordx4 v[194:197], v141, s[12:13] offset:256
	global_load_dwordx4 v[198:201], v142, s[12:13]
	global_load_dwordx4 v[202:205], v142, s[12:13] offset:256
	global_load_dwordx4 v[228:231], v143, s[12:13]
	global_load_dwordx4 v[232:235], v143, s[12:13] offset:256
	global_load_dwordx4 v[236:239], v148, s[12:13]
	global_load_dwordx4 v[156:159], v148, s[12:13] offset:256
	s_waitcnt vmcnt(13)
	v_lshlrev_b32_e32 v150, 16, v166
	v_and_b32_e32 v151, 0xffff0000, v166
	v_pk_mul_f32 v[124:125], v[124:125], v[150:151]
	v_lshlrev_b32_e32 v150, 16, v167
	v_and_b32_e32 v151, 0xffff0000, v167
	v_pk_mul_f32 v[126:127], v[126:127], v[150:151]
	v_lshlrev_b32_e32 v150, 16, v168
	v_and_b32_e32 v151, 0xffff0000, v168
	v_pk_mul_f32 v[120:121], v[120:121], v[150:151]
	v_lshlrev_b32_e32 v150, 16, v169
	v_and_b32_e32 v151, 0xffff0000, v169
	v_pk_mul_f32 v[122:123], v[122:123], v[150:151]
	v_cvt_pk_bf16_f32 v166, v124, v125
	v_cvt_pk_bf16_f32 v167, v126, v127
	v_cvt_pk_bf16_f32 v168, v120, v121
	v_cvt_pk_bf16_f32 v169, v122, v123
	global_store_dwordx4 v138, v[166:169], s[10:11]
	global_load_dwordx4 v[166:169], v149, s[12:13]
	s_waitcnt vmcnt(14)
	v_lshlrev_b32_e32 v150, 16, v170
	v_and_b32_e32 v151, 0xffff0000, v170
	v_pk_mul_f32 v[116:117], v[116:117], v[150:151]
	v_lshlrev_b32_e32 v150, 16, v171
	v_and_b32_e32 v151, 0xffff0000, v171
	v_pk_mul_f32 v[118:119], v[118:119], v[150:151]
	v_lshlrev_b32_e32 v150, 16, v172
	v_and_b32_e32 v151, 0xffff0000, v172
	v_pk_mul_f32 v[112:113], v[112:113], v[150:151]
	v_lshlrev_b32_e32 v150, 16, v173
	v_and_b32_e32 v151, 0xffff0000, v173
	v_pk_mul_f32 v[114:115], v[114:115], v[150:151]
	v_cvt_pk_bf16_f32 v170, v116, v117
	v_cvt_pk_bf16_f32 v171, v118, v119
	v_cvt_pk_bf16_f32 v172, v112, v113
	v_cvt_pk_bf16_f32 v173, v114, v115
	global_store_dwordx4 v138, v[170:173], s[10:11] offset:256
	global_load_dwordx4 v[170:173], v149, s[12:13] offset:256
	s_waitcnt vmcnt(15)
	v_lshlrev_b32_e32 v150, 16, v174
	v_and_b32_e32 v151, 0xffff0000, v174
	v_pk_mul_f32 v[108:109], v[108:109], v[150:151]
	v_lshlrev_b32_e32 v150, 16, v175
	v_and_b32_e32 v151, 0xffff0000, v175
	v_pk_mul_f32 v[110:111], v[110:111], v[150:151]
	v_lshlrev_b32_e32 v150, 16, v176
	v_and_b32_e32 v151, 0xffff0000, v176
	v_pk_mul_f32 v[104:105], v[104:105], v[150:151]
	v_lshlrev_b32_e32 v150, 16, v177
	v_and_b32_e32 v151, 0xffff0000, v177
	v_pk_mul_f32 v[106:107], v[106:107], v[150:151]
	v_cvt_pk_bf16_f32 v174, v108, v109
	v_cvt_pk_bf16_f32 v175, v110, v111
	v_cvt_pk_bf16_f32 v176, v104, v105
	v_cvt_pk_bf16_f32 v177, v106, v107
	global_store_dwordx4 v139, v[174:177], s[10:11]
	s_waitcnt vmcnt(15)
	v_lshlrev_b32_e32 v150, 16, v178
	v_and_b32_e32 v151, 0xffff0000, v178
	v_pk_mul_f32 v[100:101], v[100:101], v[150:151]
	v_lshlrev_b32_e32 v150, 16, v179
	v_and_b32_e32 v151, 0xffff0000, v179
	v_pk_mul_f32 v[102:103], v[102:103], v[150:151]
	v_lshlrev_b32_e32 v150, 16, v180
	v_and_b32_e32 v151, 0xffff0000, v180
	v_pk_mul_f32 v[96:97], v[96:97], v[150:151]
	v_lshlrev_b32_e32 v150, 16, v181
	v_and_b32_e32 v151, 0xffff0000, v181
	v_pk_mul_f32 v[98:99], v[98:99], v[150:151]
	v_cvt_pk_bf16_f32 v178, v100, v101
	v_cvt_pk_bf16_f32 v179, v102, v103
	v_cvt_pk_bf16_f32 v180, v96, v97
	v_cvt_pk_bf16_f32 v181, v98, v99
	global_store_dwordx4 v139, v[178:181], s[10:11] offset:256
	s_waitcnt vmcnt(15)
	v_lshlrev_b32_e32 v150, 16, v182
	v_and_b32_e32 v151, 0xffff0000, v182
	v_pk_mul_f32 v[92:93], v[92:93], v[150:151]
	v_lshlrev_b32_e32 v150, 16, v183
	v_and_b32_e32 v151, 0xffff0000, v183
	v_pk_mul_f32 v[94:95], v[94:95], v[150:151]
	v_lshlrev_b32_e32 v150, 16, v184
	v_and_b32_e32 v151, 0xffff0000, v184
	v_pk_mul_f32 v[88:89], v[88:89], v[150:151]
	v_lshlrev_b32_e32 v150, 16, v185
	v_and_b32_e32 v151, 0xffff0000, v185
	v_pk_mul_f32 v[90:91], v[90:91], v[150:151]
	v_cvt_pk_bf16_f32 v182, v92, v93
	v_cvt_pk_bf16_f32 v183, v94, v95
	v_cvt_pk_bf16_f32 v184, v88, v89
	v_cvt_pk_bf16_f32 v185, v90, v91
	global_store_dwordx4 v140, v[182:185], s[10:11]
	s_waitcnt vmcnt(15)
	v_lshlrev_b32_e32 v150, 16, v186
	v_and_b32_e32 v151, 0xffff0000, v186
	v_pk_mul_f32 v[84:85], v[84:85], v[150:151]
	v_lshlrev_b32_e32 v150, 16, v187
	v_and_b32_e32 v151, 0xffff0000, v187
	v_pk_mul_f32 v[86:87], v[86:87], v[150:151]
	v_lshlrev_b32_e32 v150, 16, v188
	v_and_b32_e32 v151, 0xffff0000, v188
	v_pk_mul_f32 v[80:81], v[80:81], v[150:151]
	v_lshlrev_b32_e32 v150, 16, v189
	v_and_b32_e32 v151, 0xffff0000, v189
	v_pk_mul_f32 v[82:83], v[82:83], v[150:151]
	v_cvt_pk_bf16_f32 v186, v84, v85
	v_cvt_pk_bf16_f32 v187, v86, v87
	v_cvt_pk_bf16_f32 v188, v80, v81
	v_cvt_pk_bf16_f32 v189, v82, v83
	global_store_dwordx4 v140, v[186:189], s[10:11] offset:256
	s_waitcnt vmcnt(15)
	v_lshlrev_b32_e32 v150, 16, v190
	v_and_b32_e32 v151, 0xffff0000, v190
	v_pk_mul_f32 v[76:77], v[76:77], v[150:151]
	v_lshlrev_b32_e32 v150, 16, v191
	v_and_b32_e32 v151, 0xffff0000, v191
	v_pk_mul_f32 v[78:79], v[78:79], v[150:151]
	v_lshlrev_b32_e32 v150, 16, v192
	v_and_b32_e32 v151, 0xffff0000, v192
	v_pk_mul_f32 v[72:73], v[72:73], v[150:151]
	v_lshlrev_b32_e32 v150, 16, v193
	v_and_b32_e32 v151, 0xffff0000, v193
	v_pk_mul_f32 v[74:75], v[74:75], v[150:151]
	v_cvt_pk_bf16_f32 v190, v76, v77
	v_cvt_pk_bf16_f32 v191, v78, v79
	v_cvt_pk_bf16_f32 v192, v72, v73
	v_cvt_pk_bf16_f32 v193, v74, v75
	global_store_dwordx4 v141, v[190:193], s[10:11]
	s_waitcnt vmcnt(15)
	v_lshlrev_b32_e32 v150, 16, v194
	v_and_b32_e32 v151, 0xffff0000, v194
	v_pk_mul_f32 v[68:69], v[68:69], v[150:151]
	v_lshlrev_b32_e32 v150, 16, v195
	v_and_b32_e32 v151, 0xffff0000, v195
	v_pk_mul_f32 v[70:71], v[70:71], v[150:151]
	v_lshlrev_b32_e32 v150, 16, v196
	v_and_b32_e32 v151, 0xffff0000, v196
	v_pk_mul_f32 v[64:65], v[64:65], v[150:151]
	v_lshlrev_b32_e32 v150, 16, v197
	v_and_b32_e32 v151, 0xffff0000, v197
	v_pk_mul_f32 v[66:67], v[66:67], v[150:151]
	v_cvt_pk_bf16_f32 v194, v68, v69
	v_cvt_pk_bf16_f32 v195, v70, v71
	v_cvt_pk_bf16_f32 v196, v64, v65
	v_cvt_pk_bf16_f32 v197, v66, v67
	global_store_dwordx4 v141, v[194:197], s[10:11] offset:256
	s_waitcnt vmcnt(15)
	v_lshlrev_b32_e32 v150, 16, v198
	v_and_b32_e32 v151, 0xffff0000, v198
	v_pk_mul_f32 v[60:61], v[60:61], v[150:151]
	v_lshlrev_b32_e32 v150, 16, v199
	v_and_b32_e32 v151, 0xffff0000, v199
	v_pk_mul_f32 v[62:63], v[62:63], v[150:151]
	v_lshlrev_b32_e32 v150, 16, v200
	v_and_b32_e32 v151, 0xffff0000, v200
	v_pk_mul_f32 v[56:57], v[56:57], v[150:151]
	v_lshlrev_b32_e32 v150, 16, v201
	v_and_b32_e32 v151, 0xffff0000, v201
	v_pk_mul_f32 v[58:59], v[58:59], v[150:151]
	v_cvt_pk_bf16_f32 v198, v60, v61
	v_cvt_pk_bf16_f32 v199, v62, v63
	v_cvt_pk_bf16_f32 v200, v56, v57
	v_cvt_pk_bf16_f32 v201, v58, v59
	global_store_dwordx4 v142, v[198:201], s[10:11]
	s_waitcnt vmcnt(15)
	v_lshlrev_b32_e32 v150, 16, v202
	v_and_b32_e32 v151, 0xffff0000, v202
	v_pk_mul_f32 v[52:53], v[52:53], v[150:151]
	v_lshlrev_b32_e32 v150, 16, v203
	v_and_b32_e32 v151, 0xffff0000, v203
	v_pk_mul_f32 v[54:55], v[54:55], v[150:151]
	v_lshlrev_b32_e32 v150, 16, v204
	v_and_b32_e32 v151, 0xffff0000, v204
	v_pk_mul_f32 v[48:49], v[48:49], v[150:151]
	v_lshlrev_b32_e32 v150, 16, v205
	v_and_b32_e32 v151, 0xffff0000, v205
	v_pk_mul_f32 v[50:51], v[50:51], v[150:151]
	v_cvt_pk_bf16_f32 v202, v52, v53
	v_cvt_pk_bf16_f32 v203, v54, v55
	v_cvt_pk_bf16_f32 v204, v48, v49
	v_cvt_pk_bf16_f32 v205, v50, v51
	global_store_dwordx4 v142, v[202:205], s[10:11] offset:256
	s_waitcnt vmcnt(15)
	v_lshlrev_b32_e32 v150, 16, v228
	v_and_b32_e32 v151, 0xffff0000, v228
	v_pk_mul_f32 v[44:45], v[44:45], v[150:151]
	v_lshlrev_b32_e32 v150, 16, v229
	v_and_b32_e32 v151, 0xffff0000, v229
	v_pk_mul_f32 v[46:47], v[46:47], v[150:151]
	v_lshlrev_b32_e32 v150, 16, v230
	v_and_b32_e32 v151, 0xffff0000, v230
	v_pk_mul_f32 v[40:41], v[40:41], v[150:151]
	v_lshlrev_b32_e32 v150, 16, v231
	v_and_b32_e32 v151, 0xffff0000, v231
	v_pk_mul_f32 v[42:43], v[42:43], v[150:151]
	v_cvt_pk_bf16_f32 v228, v44, v45
	v_cvt_pk_bf16_f32 v229, v46, v47
	v_cvt_pk_bf16_f32 v230, v40, v41
	v_cvt_pk_bf16_f32 v231, v42, v43
	global_store_dwordx4 v143, v[228:231], s[10:11]
	s_waitcnt vmcnt(15)
	v_lshlrev_b32_e32 v150, 16, v232
	v_and_b32_e32 v151, 0xffff0000, v232
	v_pk_mul_f32 v[36:37], v[36:37], v[150:151]
	v_lshlrev_b32_e32 v150, 16, v233
	v_and_b32_e32 v151, 0xffff0000, v233
	v_pk_mul_f32 v[38:39], v[38:39], v[150:151]
	v_lshlrev_b32_e32 v150, 16, v234
	v_and_b32_e32 v151, 0xffff0000, v234
	v_pk_mul_f32 v[32:33], v[32:33], v[150:151]
	v_lshlrev_b32_e32 v150, 16, v235
	v_and_b32_e32 v151, 0xffff0000, v235
	v_pk_mul_f32 v[34:35], v[34:35], v[150:151]
	v_cvt_pk_bf16_f32 v232, v36, v37
	v_cvt_pk_bf16_f32 v233, v38, v39
	v_cvt_pk_bf16_f32 v234, v32, v33
	v_cvt_pk_bf16_f32 v235, v34, v35
	global_store_dwordx4 v143, v[232:235], s[10:11] offset:256
	s_waitcnt vmcnt(15)
	v_lshlrev_b32_e32 v150, 16, v236
	v_and_b32_e32 v151, 0xffff0000, v236
	v_pk_mul_f32 v[28:29], v[28:29], v[150:151]
	v_lshlrev_b32_e32 v150, 16, v237
	v_and_b32_e32 v151, 0xffff0000, v237
	v_pk_mul_f32 v[30:31], v[30:31], v[150:151]
	v_lshlrev_b32_e32 v150, 16, v238
	v_and_b32_e32 v151, 0xffff0000, v238
	v_pk_mul_f32 v[24:25], v[24:25], v[150:151]
	v_lshlrev_b32_e32 v150, 16, v239
	v_and_b32_e32 v151, 0xffff0000, v239
	v_pk_mul_f32 v[26:27], v[26:27], v[150:151]
	v_cvt_pk_bf16_f32 v236, v28, v29
	v_cvt_pk_bf16_f32 v237, v30, v31
	v_cvt_pk_bf16_f32 v238, v24, v25
	v_cvt_pk_bf16_f32 v239, v26, v27
	global_store_dwordx4 v148, v[236:239], s[10:11]
	s_waitcnt vmcnt(15)
	v_lshlrev_b32_e32 v150, 16, v156
	v_and_b32_e32 v151, 0xffff0000, v156
	v_pk_mul_f32 v[20:21], v[20:21], v[150:151]
	v_lshlrev_b32_e32 v150, 16, v157
	v_and_b32_e32 v151, 0xffff0000, v157
	v_pk_mul_f32 v[22:23], v[22:23], v[150:151]
	v_lshlrev_b32_e32 v150, 16, v158
	v_and_b32_e32 v151, 0xffff0000, v158
	v_pk_mul_f32 v[16:17], v[16:17], v[150:151]
	v_lshlrev_b32_e32 v150, 16, v159
	v_and_b32_e32 v151, 0xffff0000, v159
	v_pk_mul_f32 v[18:19], v[18:19], v[150:151]
	v_cvt_pk_bf16_f32 v156, v20, v21
	v_cvt_pk_bf16_f32 v157, v22, v23
	v_cvt_pk_bf16_f32 v158, v16, v17
	v_cvt_pk_bf16_f32 v159, v18, v19
	global_store_dwordx4 v148, v[156:159], s[10:11] offset:256
	s_waitcnt vmcnt(14)
	v_lshlrev_b32_e32 v150, 16, v166
	v_and_b32_e32 v151, 0xffff0000, v166
	v_pk_mul_f32 v[12:13], v[12:13], v[150:151]
	v_lshlrev_b32_e32 v150, 16, v167
	v_and_b32_e32 v151, 0xffff0000, v167
	v_pk_mul_f32 v[14:15], v[14:15], v[150:151]
	v_lshlrev_b32_e32 v150, 16, v168
	v_and_b32_e32 v151, 0xffff0000, v168
	v_pk_mul_f32 v[8:9], v[8:9], v[150:151]
	v_lshlrev_b32_e32 v150, 16, v169
	v_and_b32_e32 v151, 0xffff0000, v169
	v_pk_mul_f32 v[10:11], v[10:11], v[150:151]
	v_cvt_pk_bf16_f32 v166, v12, v13
	v_cvt_pk_bf16_f32 v167, v14, v15
	v_cvt_pk_bf16_f32 v168, v8, v9
	v_cvt_pk_bf16_f32 v169, v10, v11
	global_store_dwordx4 v149, v[166:169], s[10:11]
	s_waitcnt vmcnt(13)
	v_lshlrev_b32_e32 v150, 16, v170
	v_and_b32_e32 v151, 0xffff0000, v170
	v_pk_mul_f32 v[4:5], v[4:5], v[150:151]
	v_lshlrev_b32_e32 v150, 16, v171
	v_and_b32_e32 v151, 0xffff0000, v171
	v_pk_mul_f32 v[6:7], v[6:7], v[150:151]
	v_lshlrev_b32_e32 v150, 16, v172
	v_and_b32_e32 v151, 0xffff0000, v172
	v_pk_mul_f32 v[0:1], v[0:1], v[150:151]
	v_lshlrev_b32_e32 v150, 16, v173
	v_and_b32_e32 v151, 0xffff0000, v173
	v_pk_mul_f32 v[2:3], v[2:3], v[150:151]
	v_cvt_pk_bf16_f32 v170, v4, v5
	v_cvt_pk_bf16_f32 v171, v6, v7
	v_cvt_pk_bf16_f32 v172, v0, v1
	v_cvt_pk_bf16_f32 v173, v2, v3
	global_store_dwordx4 v149, v[170:173], s[10:11] offset:256
	s_mov_b64 s[22:23], -1
	s_cbranch_vccnz .LBB0_119
	s_and_b64 vcc, exec, s[6:7]
	s_cbranch_vccnz .LBB0_118
	s_barrier
	s_branch .LBB0_118

.LBB0_150:
	v_lshl_add_u32 v150, s41, 8, v144
	v_lshl_add_u32 v151, s2, 8, v146
	v_lshlrev_b32_e32 v150, 10, v150
	v_add_lshl_u32 v138, v150, v151, 1
	v_add_u32_e32 v139, 0x8000, v138
	v_add_u32_e32 v140, 0x10000, v138
	v_add_u32_e32 v141, 0x18000, v138
	v_add_u32_e32 v142, 0x40000, v138
	v_add_u32_e32 v143, 0x48000, v138
	v_add_u32_e32 v148, 0x50000, v138
	v_add_u32_e32 v149, 0x58000, v138
	s_andn2_b64 vcc, exec, s[8:9]
	s_waitcnt lgkmcnt(0)
	global_load_dwordx4 v[166:169], v138, s[12:13]
	global_load_dwordx4 v[170:173], v138, s[10:11]
	global_load_dwordx4 v[174:177], v138, s[12:13] offset:256
	global_load_dwordx4 v[178:181], v138, s[10:11] offset:256
	global_load_dwordx4 v[182:185], v139, s[12:13]
	global_load_dwordx4 v[186:189], v139, s[10:11]
	global_load_dwordx4 v[190:193], v139, s[12:13] offset:256
	global_load_dwordx4 v[194:197], v139, s[10:11] offset:256
	global_load_dwordx4 v[198:201], v140, s[12:13]
	global_load_dwordx4 v[202:205], v140, s[10:11]
	global_load_dwordx4 v[228:231], v140, s[12:13] offset:256
	global_load_dwordx4 v[232:235], v140, s[10:11] offset:256
	global_load_dwordx4 v[236:239], v141, s[12:13]
	global_load_dwordx4 v[156:159], v141, s[10:11]
	s_waitcnt vmcnt(12)
	v_lshlrev_b32_e32 v150, 16, v166
	v_and_b32_e32 v151, 0xffff0000, v166
	v_lshlrev_b32_e32 v152, 16, v170
	v_and_b32_e32 v153, 0xffff0000, v170
	v_pk_fma_f32 v[124:125], v[124:125], v[150:151], v[152:153]
	v_lshlrev_b32_e32 v150, 16, v167
	v_and_b32_e32 v151, 0xffff0000, v167
	v_lshlrev_b32_e32 v152, 16, v171
	v_and_b32_e32 v153, 0xffff0000, v171
	v_pk_fma_f32 v[126:127], v[126:127], v[150:151], v[152:153]
	v_lshlrev_b32_e32 v150, 16, v168
	v_and_b32_e32 v151, 0xffff0000, v168
	v_lshlrev_b32_e32 v152, 16, v172
	v_and_b32_e32 v153, 0xffff0000, v172
	v_pk_fma_f32 v[120:121], v[120:121], v[150:151], v[152:153]
	v_lshlrev_b32_e32 v150, 16, v169
	v_and_b32_e32 v151, 0xffff0000, v169
	v_lshlrev_b32_e32 v152, 16, v173
	v_and_b32_e32 v153, 0xffff0000, v173
	v_pk_fma_f32 v[122:123], v[122:123], v[150:151], v[152:153]
	v_cvt_pk_bf16_f32 v166, v124, v125
	v_cvt_pk_bf16_f32 v167, v126, v127
	v_cvt_pk_bf16_f32 v168, v120, v121
	v_cvt_pk_bf16_f32 v169, v122, v123
	global_store_dwordx4 v138, v[166:169], s[10:11]
	global_load_dwordx4 v[166:169], v141, s[12:13] offset:256
	global_load_dwordx4 v[170:173], v141, s[10:11] offset:256
	s_waitcnt vmcnt(13)
	v_lshlrev_b32_e32 v150, 16, v174
	v_and_b32_e32 v151, 0xffff0000, v174
	v_lshlrev_b32_e32 v152, 16, v178
	v_and_b32_e32 v153, 0xffff0000, v178
	v_pk_fma_f32 v[116:117], v[116:117], v[150:151], v[152:153]
	v_lshlrev_b32_e32 v150, 16, v175
	v_and_b32_e32 v151, 0xffff0000, v175
	v_lshlrev_b32_e32 v152, 16, v179
	v_and_b32_e32 v153, 0xffff0000, v179
	v_pk_fma_f32 v[118:119], v[118:119], v[150:151], v[152:153]
	v_lshlrev_b32_e32 v150, 16, v176
	v_and_b32_e32 v151, 0xffff0000, v176
	v_lshlrev_b32_e32 v152, 16, v180
	v_and_b32_e32 v153, 0xffff0000, v180
	v_pk_fma_f32 v[112:113], v[112:113], v[150:151], v[152:153]
	v_lshlrev_b32_e32 v150, 16, v177
	v_and_b32_e32 v151, 0xffff0000, v177
	v_lshlrev_b32_e32 v152, 16, v181
	v_and_b32_e32 v153, 0xffff0000, v181
	v_pk_fma_f32 v[114:115], v[114:115], v[150:151], v[152:153]
	v_cvt_pk_bf16_f32 v174, v116, v117
	v_cvt_pk_bf16_f32 v175, v118, v119
	v_cvt_pk_bf16_f32 v176, v112, v113
	v_cvt_pk_bf16_f32 v177, v114, v115
	global_store_dwordx4 v138, v[174:177], s[10:11] offset:256
	global_load_dwordx4 v[174:177], v142, s[12:13]
	global_load_dwordx4 v[178:181], v142, s[10:11]
	s_waitcnt vmcnt(14)
	v_lshlrev_b32_e32 v150, 16, v182
	v_and_b32_e32 v151, 0xffff0000, v182
	v_lshlrev_b32_e32 v152, 16, v186
	v_and_b32_e32 v153, 0xffff0000, v186
	v_pk_fma_f32 v[108:109], v[108:109], v[150:151], v[152:153]
	v_lshlrev_b32_e32 v150, 16, v183
	v_and_b32_e32 v151, 0xffff0000, v183
	v_lshlrev_b32_e32 v152, 16, v187
	v_and_b32_e32 v153, 0xffff0000, v187
	v_pk_fma_f32 v[110:111], v[110:111], v[150:151], v[152:153]
	v_lshlrev_b32_e32 v150, 16, v184
	v_and_b32_e32 v151, 0xffff0000, v184
	v_lshlrev_b32_e32 v152, 16, v188
	v_and_b32_e32 v153, 0xffff0000, v188
	v_pk_fma_f32 v[104:105], v[104:105], v[150:151], v[152:153]
	v_lshlrev_b32_e32 v150, 16, v185
	v_and_b32_e32 v151, 0xffff0000, v185
	v_lshlrev_b32_e32 v152, 16, v189
	v_and_b32_e32 v153, 0xffff0000, v189
	v_pk_fma_f32 v[106:107], v[106:107], v[150:151], v[152:153]
	v_cvt_pk_bf16_f32 v182, v108, v109
	v_cvt_pk_bf16_f32 v183, v110, v111
	v_cvt_pk_bf16_f32 v184, v104, v105
	v_cvt_pk_bf16_f32 v185, v106, v107
	global_store_dwordx4 v139, v[182:185], s[10:11]
	global_load_dwordx4 v[182:185], v142, s[12:13] offset:256
	global_load_dwordx4 v[186:189], v142, s[10:11] offset:256
	s_waitcnt vmcnt(15)
	v_lshlrev_b32_e32 v150, 16, v190
	v_and_b32_e32 v151, 0xffff0000, v190
	v_lshlrev_b32_e32 v152, 16, v194
	v_and_b32_e32 v153, 0xffff0000, v194
	v_pk_fma_f32 v[100:101], v[100:101], v[150:151], v[152:153]
	v_lshlrev_b32_e32 v150, 16, v191
	v_and_b32_e32 v151, 0xffff0000, v191
	v_lshlrev_b32_e32 v152, 16, v195
	v_and_b32_e32 v153, 0xffff0000, v195
	v_pk_fma_f32 v[102:103], v[102:103], v[150:151], v[152:153]
	v_lshlrev_b32_e32 v150, 16, v192
	v_and_b32_e32 v151, 0xffff0000, v192
	v_lshlrev_b32_e32 v152, 16, v196
	v_and_b32_e32 v153, 0xffff0000, v196
	v_pk_fma_f32 v[96:97], v[96:97], v[150:151], v[152:153]
	v_lshlrev_b32_e32 v150, 16, v193
	v_and_b32_e32 v151, 0xffff0000, v193
	v_lshlrev_b32_e32 v152, 16, v197
	v_and_b32_e32 v153, 0xffff0000, v197
	v_pk_fma_f32 v[98:99], v[98:99], v[150:151], v[152:153]
	v_cvt_pk_bf16_f32 v190, v100, v101
	v_cvt_pk_bf16_f32 v191, v102, v103
	v_cvt_pk_bf16_f32 v192, v96, v97
	v_cvt_pk_bf16_f32 v193, v98, v99
	global_store_dwordx4 v139, v[190:193], s[10:11] offset:256
	global_load_dwordx4 v[190:193], v143, s[12:13]
	global_load_dwordx4 v[194:197], v143, s[10:11]
	s_waitcnt vmcnt(16)
	v_lshlrev_b32_e32 v150, 16, v198
	v_and_b32_e32 v151, 0xffff0000, v198
	v_lshlrev_b32_e32 v152, 16, v202
	v_and_b32_e32 v153, 0xffff0000, v202
	v_pk_fma_f32 v[92:93], v[92:93], v[150:151], v[152:153]
	v_lshlrev_b32_e32 v150, 16, v199
	v_and_b32_e32 v151, 0xffff0000, v199
	v_lshlrev_b32_e32 v152, 16, v203
	v_and_b32_e32 v153, 0xffff0000, v203
	v_pk_fma_f32 v[94:95], v[94:95], v[150:151], v[152:153]
	v_lshlrev_b32_e32 v150, 16, v200
	v_and_b32_e32 v151, 0xffff0000, v200
	v_lshlrev_b32_e32 v152, 16, v204
	v_and_b32_e32 v153, 0xffff0000, v204
	v_pk_fma_f32 v[88:89], v[88:89], v[150:151], v[152:153]
	v_lshlrev_b32_e32 v150, 16, v201
	v_and_b32_e32 v151, 0xffff0000, v201
	v_lshlrev_b32_e32 v152, 16, v205
	v_and_b32_e32 v153, 0xffff0000, v205
	v_pk_fma_f32 v[90:91], v[90:91], v[150:151], v[152:153]
	v_cvt_pk_bf16_f32 v198, v92, v93
	v_cvt_pk_bf16_f32 v199, v94, v95
	v_cvt_pk_bf16_f32 v200, v88, v89
	v_cvt_pk_bf16_f32 v201, v90, v91
	global_store_dwordx4 v140, v[198:201], s[10:11]
	global_load_dwordx4 v[198:201], v143, s[12:13] offset:256
	global_load_dwordx4 v[202:205], v143, s[10:11] offset:256
	s_waitcnt vmcnt(17)
	v_lshlrev_b32_e32 v150, 16, v228
	v_and_b32_e32 v151, 0xffff0000, v228
	v_lshlrev_b32_e32 v152, 16, v232
	v_and_b32_e32 v153, 0xffff0000, v232
	v_pk_fma_f32 v[84:85], v[84:85], v[150:151], v[152:153]
	v_lshlrev_b32_e32 v150, 16, v229
	v_and_b32_e32 v151, 0xffff0000, v229
	v_lshlrev_b32_e32 v152, 16, v233
	v_and_b32_e32 v153, 0xffff0000, v233
	v_pk_fma_f32 v[86:87], v[86:87], v[150:151], v[152:153]
	v_lshlrev_b32_e32 v150, 16, v230
	v_and_b32_e32 v151, 0xffff0000, v230
	v_lshlrev_b32_e32 v152, 16, v234
	v_and_b32_e32 v153, 0xffff0000, v234
	v_pk_fma_f32 v[80:81], v[80:81], v[150:151], v[152:153]
	v_lshlrev_b32_e32 v150, 16, v231
	v_and_b32_e32 v151, 0xffff0000, v231
	v_lshlrev_b32_e32 v152, 16, v235
	v_and_b32_e32 v153, 0xffff0000, v235
	v_pk_fma_f32 v[82:83], v[82:83], v[150:151], v[152:153]
	v_cvt_pk_bf16_f32 v228, v84, v85
	v_cvt_pk_bf16_f32 v229, v86, v87
	v_cvt_pk_bf16_f32 v230, v80, v81
	v_cvt_pk_bf16_f32 v231, v82, v83
	global_store_dwordx4 v140, v[228:231], s[10:11] offset:256
	global_load_dwordx4 v[228:231], v148, s[12:13]
	global_load_dwordx4 v[232:235], v148, s[10:11]
	s_waitcnt vmcnt(18)
	v_lshlrev_b32_e32 v150, 16, v236
	v_and_b32_e32 v151, 0xffff0000, v236
	v_lshlrev_b32_e32 v152, 16, v156
	v_and_b32_e32 v153, 0xffff0000, v156
	v_pk_fma_f32 v[76:77], v[76:77], v[150:151], v[152:153]
	v_lshlrev_b32_e32 v150, 16, v237
	v_and_b32_e32 v151, 0xffff0000, v237
	v_lshlrev_b32_e32 v152, 16, v157
	v_and_b32_e32 v153, 0xffff0000, v157
	v_pk_fma_f32 v[78:79], v[78:79], v[150:151], v[152:153]
	v_lshlrev_b32_e32 v150, 16, v238
	v_and_b32_e32 v151, 0xffff0000, v238
	v_lshlrev_b32_e32 v152, 16, v158
	v_and_b32_e32 v153, 0xffff0000, v158
	v_pk_fma_f32 v[72:73], v[72:73], v[150:151], v[152:153]
	v_lshlrev_b32_e32 v150, 16, v239
	v_and_b32_e32 v151, 0xffff0000, v239
	v_lshlrev_b32_e32 v152, 16, v159
	v_and_b32_e32 v153, 0xffff0000, v159
	v_pk_fma_f32 v[74:75], v[74:75], v[150:151], v[152:153]
	v_cvt_pk_bf16_f32 v236, v76, v77
	v_cvt_pk_bf16_f32 v237, v78, v79
	v_cvt_pk_bf16_f32 v238, v72, v73
	v_cvt_pk_bf16_f32 v239, v74, v75
	global_store_dwordx4 v141, v[236:239], s[10:11]
	global_load_dwordx4 v[236:239], v148, s[12:13] offset:256
	global_load_dwordx4 v[156:159], v148, s[10:11] offset:256
	s_waitcnt vmcnt(18)
	v_lshlrev_b32_e32 v150, 16, v166
	v_and_b32_e32 v151, 0xffff0000, v166
	v_lshlrev_b32_e32 v152, 16, v170
	v_and_b32_e32 v153, 0xffff0000, v170
	v_pk_fma_f32 v[68:69], v[68:69], v[150:151], v[152:153]
	v_lshlrev_b32_e32 v150, 16, v167
	v_and_b32_e32 v151, 0xffff0000, v167
	v_lshlrev_b32_e32 v152, 16, v171
	v_and_b32_e32 v153, 0xffff0000, v171
	v_pk_fma_f32 v[70:71], v[70:71], v[150:151], v[152:153]
	v_lshlrev_b32_e32 v150, 16, v168
	v_and_b32_e32 v151, 0xffff0000, v168
	v_lshlrev_b32_e32 v152, 16, v172
	v_and_b32_e32 v153, 0xffff0000, v172
	v_pk_fma_f32 v[64:65], v[64:65], v[150:151], v[152:153]
	v_lshlrev_b32_e32 v150, 16, v169
	v_and_b32_e32 v151, 0xffff0000, v169
	v_lshlrev_b32_e32 v152, 16, v173
	v_and_b32_e32 v153, 0xffff0000, v173
	v_pk_fma_f32 v[66:67], v[66:67], v[150:151], v[152:153]
	v_cvt_pk_bf16_f32 v166, v68, v69
	v_cvt_pk_bf16_f32 v167, v70, v71
	v_cvt_pk_bf16_f32 v168, v64, v65
	v_cvt_pk_bf16_f32 v169, v66, v67
	global_store_dwordx4 v141, v[166:169], s[10:11] offset:256
	global_load_dwordx4 v[166:169], v149, s[12:13]
	global_load_dwordx4 v[170:173], v149, s[10:11]
	s_waitcnt vmcnt(18)
	v_lshlrev_b32_e32 v150, 16, v174
	v_and_b32_e32 v151, 0xffff0000, v174
	v_lshlrev_b32_e32 v152, 16, v178
	v_and_b32_e32 v153, 0xffff0000, v178
	v_pk_fma_f32 v[60:61], v[60:61], v[150:151], v[152:153]
	v_lshlrev_b32_e32 v150, 16, v175
	v_and_b32_e32 v151, 0xffff0000, v175
	v_lshlrev_b32_e32 v152, 16, v179
	v_and_b32_e32 v153, 0xffff0000, v179
	v_pk_fma_f32 v[62:63], v[62:63], v[150:151], v[152:153]
	v_lshlrev_b32_e32 v150, 16, v176
	v_and_b32_e32 v151, 0xffff0000, v176
	v_lshlrev_b32_e32 v152, 16, v180
	v_and_b32_e32 v153, 0xffff0000, v180
	v_pk_fma_f32 v[56:57], v[56:57], v[150:151], v[152:153]
	v_lshlrev_b32_e32 v150, 16, v177
	v_and_b32_e32 v151, 0xffff0000, v177
	v_lshlrev_b32_e32 v152, 16, v181
	v_and_b32_e32 v153, 0xffff0000, v181
	v_pk_fma_f32 v[58:59], v[58:59], v[150:151], v[152:153]
	v_cvt_pk_bf16_f32 v174, v60, v61
	v_cvt_pk_bf16_f32 v175, v62, v63
	v_cvt_pk_bf16_f32 v176, v56, v57
	v_cvt_pk_bf16_f32 v177, v58, v59
	global_store_dwordx4 v142, v[174:177], s[10:11]
	global_load_dwordx4 v[174:177], v149, s[12:13] offset:256
	global_load_dwordx4 v[178:181], v149, s[10:11] offset:256
	s_waitcnt vmcnt(18)
	v_lshlrev_b32_e32 v150, 16, v182
	v_and_b32_e32 v151, 0xffff0000, v182
	v_lshlrev_b32_e32 v152, 16, v186
	v_and_b32_e32 v153, 0xffff0000, v186
	v_pk_fma_f32 v[52:53], v[52:53], v[150:151], v[152:153]
	v_lshlrev_b32_e32 v150, 16, v183
	v_and_b32_e32 v151, 0xffff0000, v183
	v_lshlrev_b32_e32 v152, 16, v187
	v_and_b32_e32 v153, 0xffff0000, v187
	v_pk_fma_f32 v[54:55], v[54:55], v[150:151], v[152:153]
	v_lshlrev_b32_e32 v150, 16, v184
	v_and_b32_e32 v151, 0xffff0000, v184
	v_lshlrev_b32_e32 v152, 16, v188
	v_and_b32_e32 v153, 0xffff0000, v188
	v_pk_fma_f32 v[48:49], v[48:49], v[150:151], v[152:153]
	v_lshlrev_b32_e32 v150, 16, v185
	v_and_b32_e32 v151, 0xffff0000, v185
	v_lshlrev_b32_e32 v152, 16, v189
	v_and_b32_e32 v153, 0xffff0000, v189
	v_pk_fma_f32 v[50:51], v[50:51], v[150:151], v[152:153]
	v_cvt_pk_bf16_f32 v182, v52, v53
	v_cvt_pk_bf16_f32 v183, v54, v55
	v_cvt_pk_bf16_f32 v184, v48, v49
	v_cvt_pk_bf16_f32 v185, v50, v51
	global_store_dwordx4 v142, v[182:185], s[10:11] offset:256
	s_waitcnt vmcnt(16)
	v_lshlrev_b32_e32 v150, 16, v190
	v_and_b32_e32 v151, 0xffff0000, v190
	v_lshlrev_b32_e32 v152, 16, v194
	v_and_b32_e32 v153, 0xffff0000, v194
	v_pk_fma_f32 v[44:45], v[44:45], v[150:151], v[152:153]
	v_lshlrev_b32_e32 v150, 16, v191
	v_and_b32_e32 v151, 0xffff0000, v191
	v_lshlrev_b32_e32 v152, 16, v195
	v_and_b32_e32 v153, 0xffff0000, v195
	v_pk_fma_f32 v[46:47], v[46:47], v[150:151], v[152:153]
	v_lshlrev_b32_e32 v150, 16, v192
	v_and_b32_e32 v151, 0xffff0000, v192
	v_lshlrev_b32_e32 v152, 16, v196
	v_and_b32_e32 v153, 0xffff0000, v196
	v_pk_fma_f32 v[40:41], v[40:41], v[150:151], v[152:153]
	v_lshlrev_b32_e32 v150, 16, v193
	v_and_b32_e32 v151, 0xffff0000, v193
	v_lshlrev_b32_e32 v152, 16, v197
	v_and_b32_e32 v153, 0xffff0000, v197
	v_pk_fma_f32 v[42:43], v[42:43], v[150:151], v[152:153]
	v_cvt_pk_bf16_f32 v190, v44, v45
	v_cvt_pk_bf16_f32 v191, v46, v47
	v_cvt_pk_bf16_f32 v192, v40, v41
	v_cvt_pk_bf16_f32 v193, v42, v43
	global_store_dwordx4 v143, v[190:193], s[10:11]
	s_waitcnt vmcnt(14)
	v_lshlrev_b32_e32 v150, 16, v198
	v_and_b32_e32 v151, 0xffff0000, v198
	v_lshlrev_b32_e32 v152, 16, v202
	v_and_b32_e32 v153, 0xffff0000, v202
	v_pk_fma_f32 v[36:37], v[36:37], v[150:151], v[152:153]
	v_lshlrev_b32_e32 v150, 16, v199
	v_and_b32_e32 v151, 0xffff0000, v199
	v_lshlrev_b32_e32 v152, 16, v203
	v_and_b32_e32 v153, 0xffff0000, v203
	v_pk_fma_f32 v[38:39], v[38:39], v[150:151], v[152:153]
	v_lshlrev_b32_e32 v150, 16, v200
	v_and_b32_e32 v151, 0xffff0000, v200
	v_lshlrev_b32_e32 v152, 16, v204
	v_and_b32_e32 v153, 0xffff0000, v204
	v_pk_fma_f32 v[32:33], v[32:33], v[150:151], v[152:153]
	v_lshlrev_b32_e32 v150, 16, v201
	v_and_b32_e32 v151, 0xffff0000, v201
	v_lshlrev_b32_e32 v152, 16, v205
	v_and_b32_e32 v153, 0xffff0000, v205
	v_pk_fma_f32 v[34:35], v[34:35], v[150:151], v[152:153]
	v_cvt_pk_bf16_f32 v198, v36, v37
	v_cvt_pk_bf16_f32 v199, v38, v39
	v_cvt_pk_bf16_f32 v200, v32, v33
	v_cvt_pk_bf16_f32 v201, v34, v35
	global_store_dwordx4 v143, v[198:201], s[10:11] offset:256
	s_waitcnt vmcnt(12)
	v_lshlrev_b32_e32 v150, 16, v228
	v_and_b32_e32 v151, 0xffff0000, v228
	v_lshlrev_b32_e32 v152, 16, v232
	v_and_b32_e32 v153, 0xffff0000, v232
	v_pk_fma_f32 v[28:29], v[28:29], v[150:151], v[152:153]
	v_lshlrev_b32_e32 v150, 16, v229
	v_and_b32_e32 v151, 0xffff0000, v229
	v_lshlrev_b32_e32 v152, 16, v233
	v_and_b32_e32 v153, 0xffff0000, v233
	v_pk_fma_f32 v[30:31], v[30:31], v[150:151], v[152:153]
	v_lshlrev_b32_e32 v150, 16, v230
	v_and_b32_e32 v151, 0xffff0000, v230
	v_lshlrev_b32_e32 v152, 16, v234
	v_and_b32_e32 v153, 0xffff0000, v234
	v_pk_fma_f32 v[24:25], v[24:25], v[150:151], v[152:153]
	v_lshlrev_b32_e32 v150, 16, v231
	v_and_b32_e32 v151, 0xffff0000, v231
	v_lshlrev_b32_e32 v152, 16, v235
	v_and_b32_e32 v153, 0xffff0000, v235
	v_pk_fma_f32 v[26:27], v[26:27], v[150:151], v[152:153]
	v_cvt_pk_bf16_f32 v228, v28, v29
	v_cvt_pk_bf16_f32 v229, v30, v31
	v_cvt_pk_bf16_f32 v230, v24, v25
	v_cvt_pk_bf16_f32 v231, v26, v27
	global_store_dwordx4 v148, v[228:231], s[10:11]
	s_waitcnt vmcnt(10)
	v_lshlrev_b32_e32 v150, 16, v236
	v_and_b32_e32 v151, 0xffff0000, v236
	v_lshlrev_b32_e32 v152, 16, v156
	v_and_b32_e32 v153, 0xffff0000, v156
	v_pk_fma_f32 v[20:21], v[20:21], v[150:151], v[152:153]
	v_lshlrev_b32_e32 v150, 16, v237
	v_and_b32_e32 v151, 0xffff0000, v237
	v_lshlrev_b32_e32 v152, 16, v157
	v_and_b32_e32 v153, 0xffff0000, v157
	v_pk_fma_f32 v[22:23], v[22:23], v[150:151], v[152:153]
	v_lshlrev_b32_e32 v150, 16, v238
	v_and_b32_e32 v151, 0xffff0000, v238
	v_lshlrev_b32_e32 v152, 16, v158
	v_and_b32_e32 v153, 0xffff0000, v158
	v_pk_fma_f32 v[16:17], v[16:17], v[150:151], v[152:153]
	v_lshlrev_b32_e32 v150, 16, v239
	v_and_b32_e32 v151, 0xffff0000, v239
	v_lshlrev_b32_e32 v152, 16, v159
	v_and_b32_e32 v153, 0xffff0000, v159
	v_pk_fma_f32 v[18:19], v[18:19], v[150:151], v[152:153]
	v_cvt_pk_bf16_f32 v236, v20, v21
	v_cvt_pk_bf16_f32 v237, v22, v23
	v_cvt_pk_bf16_f32 v238, v16, v17
	v_cvt_pk_bf16_f32 v239, v18, v19
	global_store_dwordx4 v148, v[236:239], s[10:11] offset:256
	s_waitcnt vmcnt(8)
	v_lshlrev_b32_e32 v150, 16, v166
	v_and_b32_e32 v151, 0xffff0000, v166
	v_lshlrev_b32_e32 v152, 16, v170
	v_and_b32_e32 v153, 0xffff0000, v170
	v_pk_fma_f32 v[12:13], v[12:13], v[150:151], v[152:153]
	v_lshlrev_b32_e32 v150, 16, v167
	v_and_b32_e32 v151, 0xffff0000, v167
	v_lshlrev_b32_e32 v152, 16, v171
	v_and_b32_e32 v153, 0xffff0000, v171
	v_pk_fma_f32 v[14:15], v[14:15], v[150:151], v[152:153]
	v_lshlrev_b32_e32 v150, 16, v168
	v_and_b32_e32 v151, 0xffff0000, v168
	v_lshlrev_b32_e32 v152, 16, v172
	v_and_b32_e32 v153, 0xffff0000, v172
	v_pk_fma_f32 v[8:9], v[8:9], v[150:151], v[152:153]
	v_lshlrev_b32_e32 v150, 16, v169
	v_and_b32_e32 v151, 0xffff0000, v169
	v_lshlrev_b32_e32 v152, 16, v173
	v_and_b32_e32 v153, 0xffff0000, v173
	v_pk_fma_f32 v[10:11], v[10:11], v[150:151], v[152:153]
	v_cvt_pk_bf16_f32 v166, v12, v13
	v_cvt_pk_bf16_f32 v167, v14, v15
	v_cvt_pk_bf16_f32 v168, v8, v9
	v_cvt_pk_bf16_f32 v169, v10, v11
	global_store_dwordx4 v149, v[166:169], s[10:11]
	s_waitcnt vmcnt(6)
	v_lshlrev_b32_e32 v150, 16, v174
	v_and_b32_e32 v151, 0xffff0000, v174
	v_lshlrev_b32_e32 v152, 16, v178
	v_and_b32_e32 v153, 0xffff0000, v178
	v_pk_fma_f32 v[4:5], v[4:5], v[150:151], v[152:153]
	v_lshlrev_b32_e32 v150, 16, v175
	v_and_b32_e32 v151, 0xffff0000, v175
	v_lshlrev_b32_e32 v152, 16, v179
	v_and_b32_e32 v153, 0xffff0000, v179
	v_pk_fma_f32 v[6:7], v[6:7], v[150:151], v[152:153]
	v_lshlrev_b32_e32 v150, 16, v176
	v_and_b32_e32 v151, 0xffff0000, v176
	v_lshlrev_b32_e32 v152, 16, v180
	v_and_b32_e32 v153, 0xffff0000, v180
	v_pk_fma_f32 v[0:1], v[0:1], v[150:151], v[152:153]
	v_lshlrev_b32_e32 v150, 16, v177
	v_and_b32_e32 v151, 0xffff0000, v177
	v_lshlrev_b32_e32 v152, 16, v181
	v_and_b32_e32 v153, 0xffff0000, v181
	v_pk_fma_f32 v[2:3], v[2:3], v[150:151], v[152:153]
	v_cvt_pk_bf16_f32 v174, v4, v5
	v_cvt_pk_bf16_f32 v175, v6, v7
	v_cvt_pk_bf16_f32 v176, v0, v1
	v_cvt_pk_bf16_f32 v177, v2, v3
	global_store_dwordx4 v149, v[174:177], s[10:11] offset:256
	s_mov_b64 s[22:23], -1
	s_cbranch_vccnz .LBB0_139
	s_and_b64 vcc, exec, s[6:7]
	s_cbranch_vccnz .LBB0_138
	s_barrier
	s_branch .LBB0_138

.LBB0_170:
	v_lshl_add_u32 v150, s39, 8, v144
	v_lshl_add_u32 v151, s2, 8, v146
	v_lshlrev_b32_e32 v150, 10, v150
	v_add_lshl_u32 v138, v150, v151, 1
	v_add_u32_e32 v139, 0x8000, v138
	v_add_u32_e32 v140, 0x10000, v138
	v_add_u32_e32 v141, 0x18000, v138
	v_add_u32_e32 v142, 0x40000, v138
	v_add_u32_e32 v143, 0x48000, v138
	v_add_u32_e32 v148, 0x50000, v138
	v_add_u32_e32 v149, 0x58000, v138
	s_andn2_b64 vcc, exec, s[6:7]
	s_waitcnt lgkmcnt(0)
	global_load_dwordx4 v[166:169], v138, s[10:11]
	global_load_dwordx4 v[170:173], v138, s[8:9]
	global_load_dwordx4 v[174:177], v138, s[10:11] offset:256
	global_load_dwordx4 v[178:181], v138, s[8:9] offset:256
	global_load_dwordx4 v[182:185], v139, s[10:11]
	global_load_dwordx4 v[186:189], v139, s[8:9]
	global_load_dwordx4 v[190:193], v139, s[10:11] offset:256
	global_load_dwordx4 v[194:197], v139, s[8:9] offset:256
	global_load_dwordx4 v[198:201], v140, s[10:11]
	global_load_dwordx4 v[202:205], v140, s[8:9]
	global_load_dwordx4 v[228:231], v140, s[10:11] offset:256
	global_load_dwordx4 v[232:235], v140, s[8:9] offset:256
	global_load_dwordx4 v[236:239], v141, s[10:11]
	global_load_dwordx4 v[156:159], v141, s[8:9]
	s_waitcnt vmcnt(12)
	v_lshlrev_b32_e32 v150, 16, v166
	v_and_b32_e32 v151, 0xffff0000, v166
	v_lshlrev_b32_e32 v152, 16, v170
	v_and_b32_e32 v153, 0xffff0000, v170
	v_pk_fma_f32 v[124:125], v[124:125], v[150:151], v[152:153]
	v_lshlrev_b32_e32 v150, 16, v167
	v_and_b32_e32 v151, 0xffff0000, v167
	v_lshlrev_b32_e32 v152, 16, v171
	v_and_b32_e32 v153, 0xffff0000, v171
	v_pk_fma_f32 v[126:127], v[126:127], v[150:151], v[152:153]
	v_lshlrev_b32_e32 v150, 16, v168
	v_and_b32_e32 v151, 0xffff0000, v168
	v_lshlrev_b32_e32 v152, 16, v172
	v_and_b32_e32 v153, 0xffff0000, v172
	v_pk_fma_f32 v[120:121], v[120:121], v[150:151], v[152:153]
	v_lshlrev_b32_e32 v150, 16, v169
	v_and_b32_e32 v151, 0xffff0000, v169
	v_lshlrev_b32_e32 v152, 16, v173
	v_and_b32_e32 v153, 0xffff0000, v173
	v_pk_fma_f32 v[122:123], v[122:123], v[150:151], v[152:153]
	v_cvt_pk_bf16_f32 v166, v124, v125
	v_cvt_pk_bf16_f32 v167, v126, v127
	v_cvt_pk_bf16_f32 v168, v120, v121
	v_cvt_pk_bf16_f32 v169, v122, v123
	global_store_dwordx4 v138, v[166:169], s[8:9]
	global_load_dwordx4 v[166:169], v141, s[10:11] offset:256
	global_load_dwordx4 v[170:173], v141, s[8:9] offset:256
	s_waitcnt vmcnt(13)
	v_lshlrev_b32_e32 v150, 16, v174
	v_and_b32_e32 v151, 0xffff0000, v174
	v_lshlrev_b32_e32 v152, 16, v178
	v_and_b32_e32 v153, 0xffff0000, v178
	v_pk_fma_f32 v[116:117], v[116:117], v[150:151], v[152:153]
	v_lshlrev_b32_e32 v150, 16, v175
	v_and_b32_e32 v151, 0xffff0000, v175
	v_lshlrev_b32_e32 v152, 16, v179
	v_and_b32_e32 v153, 0xffff0000, v179
	v_pk_fma_f32 v[118:119], v[118:119], v[150:151], v[152:153]
	v_lshlrev_b32_e32 v150, 16, v176
	v_and_b32_e32 v151, 0xffff0000, v176
	v_lshlrev_b32_e32 v152, 16, v180
	v_and_b32_e32 v153, 0xffff0000, v180
	v_pk_fma_f32 v[112:113], v[112:113], v[150:151], v[152:153]
	v_lshlrev_b32_e32 v150, 16, v177
	v_and_b32_e32 v151, 0xffff0000, v177
	v_lshlrev_b32_e32 v152, 16, v181
	v_and_b32_e32 v153, 0xffff0000, v181
	v_pk_fma_f32 v[114:115], v[114:115], v[150:151], v[152:153]
	v_cvt_pk_bf16_f32 v174, v116, v117
	v_cvt_pk_bf16_f32 v175, v118, v119
	v_cvt_pk_bf16_f32 v176, v112, v113
	v_cvt_pk_bf16_f32 v177, v114, v115
	global_store_dwordx4 v138, v[174:177], s[8:9] offset:256
	global_load_dwordx4 v[174:177], v142, s[10:11]
	global_load_dwordx4 v[178:181], v142, s[8:9]
	s_waitcnt vmcnt(14)
	v_lshlrev_b32_e32 v150, 16, v182
	v_and_b32_e32 v151, 0xffff0000, v182
	v_lshlrev_b32_e32 v152, 16, v186
	v_and_b32_e32 v153, 0xffff0000, v186
	v_pk_fma_f32 v[108:109], v[108:109], v[150:151], v[152:153]
	v_lshlrev_b32_e32 v150, 16, v183
	v_and_b32_e32 v151, 0xffff0000, v183
	v_lshlrev_b32_e32 v152, 16, v187
	v_and_b32_e32 v153, 0xffff0000, v187
	v_pk_fma_f32 v[110:111], v[110:111], v[150:151], v[152:153]
	v_lshlrev_b32_e32 v150, 16, v184
	v_and_b32_e32 v151, 0xffff0000, v184
	v_lshlrev_b32_e32 v152, 16, v188
	v_and_b32_e32 v153, 0xffff0000, v188
	v_pk_fma_f32 v[104:105], v[104:105], v[150:151], v[152:153]
	v_lshlrev_b32_e32 v150, 16, v185
	v_and_b32_e32 v151, 0xffff0000, v185
	v_lshlrev_b32_e32 v152, 16, v189
	v_and_b32_e32 v153, 0xffff0000, v189
	v_pk_fma_f32 v[106:107], v[106:107], v[150:151], v[152:153]
	v_cvt_pk_bf16_f32 v182, v108, v109
	v_cvt_pk_bf16_f32 v183, v110, v111
	v_cvt_pk_bf16_f32 v184, v104, v105
	v_cvt_pk_bf16_f32 v185, v106, v107
	global_store_dwordx4 v139, v[182:185], s[8:9]
	global_load_dwordx4 v[182:185], v142, s[10:11] offset:256
	global_load_dwordx4 v[186:189], v142, s[8:9] offset:256
	s_waitcnt vmcnt(15)
	v_lshlrev_b32_e32 v150, 16, v190
	v_and_b32_e32 v151, 0xffff0000, v190
	v_lshlrev_b32_e32 v152, 16, v194
	v_and_b32_e32 v153, 0xffff0000, v194
	v_pk_fma_f32 v[100:101], v[100:101], v[150:151], v[152:153]
	v_lshlrev_b32_e32 v150, 16, v191
	v_and_b32_e32 v151, 0xffff0000, v191
	v_lshlrev_b32_e32 v152, 16, v195
	v_and_b32_e32 v153, 0xffff0000, v195
	v_pk_fma_f32 v[102:103], v[102:103], v[150:151], v[152:153]
	v_lshlrev_b32_e32 v150, 16, v192
	v_and_b32_e32 v151, 0xffff0000, v192
	v_lshlrev_b32_e32 v152, 16, v196
	v_and_b32_e32 v153, 0xffff0000, v196
	v_pk_fma_f32 v[96:97], v[96:97], v[150:151], v[152:153]
	v_lshlrev_b32_e32 v150, 16, v193
	v_and_b32_e32 v151, 0xffff0000, v193
	v_lshlrev_b32_e32 v152, 16, v197
	v_and_b32_e32 v153, 0xffff0000, v197
	v_pk_fma_f32 v[98:99], v[98:99], v[150:151], v[152:153]
	v_cvt_pk_bf16_f32 v190, v100, v101
	v_cvt_pk_bf16_f32 v191, v102, v103
	v_cvt_pk_bf16_f32 v192, v96, v97
	v_cvt_pk_bf16_f32 v193, v98, v99
	global_store_dwordx4 v139, v[190:193], s[8:9] offset:256
	global_load_dwordx4 v[190:193], v143, s[10:11]
	global_load_dwordx4 v[194:197], v143, s[8:9]
	s_waitcnt vmcnt(16)
	v_lshlrev_b32_e32 v150, 16, v198
	v_and_b32_e32 v151, 0xffff0000, v198
	v_lshlrev_b32_e32 v152, 16, v202
	v_and_b32_e32 v153, 0xffff0000, v202
	v_pk_fma_f32 v[92:93], v[92:93], v[150:151], v[152:153]
	v_lshlrev_b32_e32 v150, 16, v199
	v_and_b32_e32 v151, 0xffff0000, v199
	v_lshlrev_b32_e32 v152, 16, v203
	v_and_b32_e32 v153, 0xffff0000, v203
	v_pk_fma_f32 v[94:95], v[94:95], v[150:151], v[152:153]
	v_lshlrev_b32_e32 v150, 16, v200
	v_and_b32_e32 v151, 0xffff0000, v200
	v_lshlrev_b32_e32 v152, 16, v204
	v_and_b32_e32 v153, 0xffff0000, v204
	v_pk_fma_f32 v[88:89], v[88:89], v[150:151], v[152:153]
	v_lshlrev_b32_e32 v150, 16, v201
	v_and_b32_e32 v151, 0xffff0000, v201
	v_lshlrev_b32_e32 v152, 16, v205
	v_and_b32_e32 v153, 0xffff0000, v205
	v_pk_fma_f32 v[90:91], v[90:91], v[150:151], v[152:153]
	v_cvt_pk_bf16_f32 v198, v92, v93
	v_cvt_pk_bf16_f32 v199, v94, v95
	v_cvt_pk_bf16_f32 v200, v88, v89
	v_cvt_pk_bf16_f32 v201, v90, v91
	global_store_dwordx4 v140, v[198:201], s[8:9]
	global_load_dwordx4 v[198:201], v143, s[10:11] offset:256
	global_load_dwordx4 v[202:205], v143, s[8:9] offset:256
	s_waitcnt vmcnt(17)
	v_lshlrev_b32_e32 v150, 16, v228
	v_and_b32_e32 v151, 0xffff0000, v228
	v_lshlrev_b32_e32 v152, 16, v232
	v_and_b32_e32 v153, 0xffff0000, v232
	v_pk_fma_f32 v[84:85], v[84:85], v[150:151], v[152:153]
	v_lshlrev_b32_e32 v150, 16, v229
	v_and_b32_e32 v151, 0xffff0000, v229
	v_lshlrev_b32_e32 v152, 16, v233
	v_and_b32_e32 v153, 0xffff0000, v233
	v_pk_fma_f32 v[86:87], v[86:87], v[150:151], v[152:153]
	v_lshlrev_b32_e32 v150, 16, v230
	v_and_b32_e32 v151, 0xffff0000, v230
	v_lshlrev_b32_e32 v152, 16, v234
	v_and_b32_e32 v153, 0xffff0000, v234
	v_pk_fma_f32 v[80:81], v[80:81], v[150:151], v[152:153]
	v_lshlrev_b32_e32 v150, 16, v231
	v_and_b32_e32 v151, 0xffff0000, v231
	v_lshlrev_b32_e32 v152, 16, v235
	v_and_b32_e32 v153, 0xffff0000, v235
	v_pk_fma_f32 v[82:83], v[82:83], v[150:151], v[152:153]
	v_cvt_pk_bf16_f32 v228, v84, v85
	v_cvt_pk_bf16_f32 v229, v86, v87
	v_cvt_pk_bf16_f32 v230, v80, v81
	v_cvt_pk_bf16_f32 v231, v82, v83
	global_store_dwordx4 v140, v[228:231], s[8:9] offset:256
	global_load_dwordx4 v[228:231], v148, s[10:11]
	global_load_dwordx4 v[232:235], v148, s[8:9]
	s_waitcnt vmcnt(18)
	v_lshlrev_b32_e32 v150, 16, v236
	v_and_b32_e32 v151, 0xffff0000, v236
	v_lshlrev_b32_e32 v152, 16, v156
	v_and_b32_e32 v153, 0xffff0000, v156
	v_pk_fma_f32 v[76:77], v[76:77], v[150:151], v[152:153]
	v_lshlrev_b32_e32 v150, 16, v237
	v_and_b32_e32 v151, 0xffff0000, v237
	v_lshlrev_b32_e32 v152, 16, v157
	v_and_b32_e32 v153, 0xffff0000, v157
	v_pk_fma_f32 v[78:79], v[78:79], v[150:151], v[152:153]
	v_lshlrev_b32_e32 v150, 16, v238
	v_and_b32_e32 v151, 0xffff0000, v238
	v_lshlrev_b32_e32 v152, 16, v158
	v_and_b32_e32 v153, 0xffff0000, v158
	v_pk_fma_f32 v[72:73], v[72:73], v[150:151], v[152:153]
	v_lshlrev_b32_e32 v150, 16, v239
	v_and_b32_e32 v151, 0xffff0000, v239
	v_lshlrev_b32_e32 v152, 16, v159
	v_and_b32_e32 v153, 0xffff0000, v159
	v_pk_fma_f32 v[74:75], v[74:75], v[150:151], v[152:153]
	v_cvt_pk_bf16_f32 v236, v76, v77
	v_cvt_pk_bf16_f32 v237, v78, v79
	v_cvt_pk_bf16_f32 v238, v72, v73
	v_cvt_pk_bf16_f32 v239, v74, v75
	global_store_dwordx4 v141, v[236:239], s[8:9]
	global_load_dwordx4 v[236:239], v148, s[10:11] offset:256
	global_load_dwordx4 v[156:159], v148, s[8:9] offset:256
	s_waitcnt vmcnt(18)
	v_lshlrev_b32_e32 v150, 16, v166
	v_and_b32_e32 v151, 0xffff0000, v166
	v_lshlrev_b32_e32 v152, 16, v170
	v_and_b32_e32 v153, 0xffff0000, v170
	v_pk_fma_f32 v[68:69], v[68:69], v[150:151], v[152:153]
	v_lshlrev_b32_e32 v150, 16, v167
	v_and_b32_e32 v151, 0xffff0000, v167
	v_lshlrev_b32_e32 v152, 16, v171
	v_and_b32_e32 v153, 0xffff0000, v171
	v_pk_fma_f32 v[70:71], v[70:71], v[150:151], v[152:153]
	v_lshlrev_b32_e32 v150, 16, v168
	v_and_b32_e32 v151, 0xffff0000, v168
	v_lshlrev_b32_e32 v152, 16, v172
	v_and_b32_e32 v153, 0xffff0000, v172
	v_pk_fma_f32 v[64:65], v[64:65], v[150:151], v[152:153]
	v_lshlrev_b32_e32 v150, 16, v169
	v_and_b32_e32 v151, 0xffff0000, v169
	v_lshlrev_b32_e32 v152, 16, v173
	v_and_b32_e32 v153, 0xffff0000, v173
	v_pk_fma_f32 v[66:67], v[66:67], v[150:151], v[152:153]
	v_cvt_pk_bf16_f32 v166, v68, v69
	v_cvt_pk_bf16_f32 v167, v70, v71
	v_cvt_pk_bf16_f32 v168, v64, v65
	v_cvt_pk_bf16_f32 v169, v66, v67
	global_store_dwordx4 v141, v[166:169], s[8:9] offset:256
	global_load_dwordx4 v[166:169], v149, s[10:11]
	global_load_dwordx4 v[170:173], v149, s[8:9]
	s_waitcnt vmcnt(18)
	v_lshlrev_b32_e32 v150, 16, v174
	v_and_b32_e32 v151, 0xffff0000, v174
	v_lshlrev_b32_e32 v152, 16, v178
	v_and_b32_e32 v153, 0xffff0000, v178
	v_pk_fma_f32 v[60:61], v[60:61], v[150:151], v[152:153]
	v_lshlrev_b32_e32 v150, 16, v175
	v_and_b32_e32 v151, 0xffff0000, v175
	v_lshlrev_b32_e32 v152, 16, v179
	v_and_b32_e32 v153, 0xffff0000, v179
	v_pk_fma_f32 v[62:63], v[62:63], v[150:151], v[152:153]
	v_lshlrev_b32_e32 v150, 16, v176
	v_and_b32_e32 v151, 0xffff0000, v176
	v_lshlrev_b32_e32 v152, 16, v180
	v_and_b32_e32 v153, 0xffff0000, v180
	v_pk_fma_f32 v[56:57], v[56:57], v[150:151], v[152:153]
	v_lshlrev_b32_e32 v150, 16, v177
	v_and_b32_e32 v151, 0xffff0000, v177
	v_lshlrev_b32_e32 v152, 16, v181
	v_and_b32_e32 v153, 0xffff0000, v181
	v_pk_fma_f32 v[58:59], v[58:59], v[150:151], v[152:153]
	v_cvt_pk_bf16_f32 v174, v60, v61
	v_cvt_pk_bf16_f32 v175, v62, v63
	v_cvt_pk_bf16_f32 v176, v56, v57
	v_cvt_pk_bf16_f32 v177, v58, v59
	global_store_dwordx4 v142, v[174:177], s[8:9]
	global_load_dwordx4 v[174:177], v149, s[10:11] offset:256
	global_load_dwordx4 v[178:181], v149, s[8:9] offset:256
	s_waitcnt vmcnt(18)
	v_lshlrev_b32_e32 v150, 16, v182
	v_and_b32_e32 v151, 0xffff0000, v182
	v_lshlrev_b32_e32 v152, 16, v186
	v_and_b32_e32 v153, 0xffff0000, v186
	v_pk_fma_f32 v[52:53], v[52:53], v[150:151], v[152:153]
	v_lshlrev_b32_e32 v150, 16, v183
	v_and_b32_e32 v151, 0xffff0000, v183
	v_lshlrev_b32_e32 v152, 16, v187
	v_and_b32_e32 v153, 0xffff0000, v187
	v_pk_fma_f32 v[54:55], v[54:55], v[150:151], v[152:153]
	v_lshlrev_b32_e32 v150, 16, v184
	v_and_b32_e32 v151, 0xffff0000, v184
	v_lshlrev_b32_e32 v152, 16, v188
	v_and_b32_e32 v153, 0xffff0000, v188
	v_pk_fma_f32 v[48:49], v[48:49], v[150:151], v[152:153]
	v_lshlrev_b32_e32 v150, 16, v185
	v_and_b32_e32 v151, 0xffff0000, v185
	v_lshlrev_b32_e32 v152, 16, v189
	v_and_b32_e32 v153, 0xffff0000, v189
	v_pk_fma_f32 v[50:51], v[50:51], v[150:151], v[152:153]
	v_cvt_pk_bf16_f32 v182, v52, v53
	v_cvt_pk_bf16_f32 v183, v54, v55
	v_cvt_pk_bf16_f32 v184, v48, v49
	v_cvt_pk_bf16_f32 v185, v50, v51
	global_store_dwordx4 v142, v[182:185], s[8:9] offset:256
	s_waitcnt vmcnt(16)
	v_lshlrev_b32_e32 v150, 16, v190
	v_and_b32_e32 v151, 0xffff0000, v190
	v_lshlrev_b32_e32 v152, 16, v194
	v_and_b32_e32 v153, 0xffff0000, v194
	v_pk_fma_f32 v[44:45], v[44:45], v[150:151], v[152:153]
	v_lshlrev_b32_e32 v150, 16, v191
	v_and_b32_e32 v151, 0xffff0000, v191
	v_lshlrev_b32_e32 v152, 16, v195
	v_and_b32_e32 v153, 0xffff0000, v195
	v_pk_fma_f32 v[46:47], v[46:47], v[150:151], v[152:153]
	v_lshlrev_b32_e32 v150, 16, v192
	v_and_b32_e32 v151, 0xffff0000, v192
	v_lshlrev_b32_e32 v152, 16, v196
	v_and_b32_e32 v153, 0xffff0000, v196
	v_pk_fma_f32 v[40:41], v[40:41], v[150:151], v[152:153]
	v_lshlrev_b32_e32 v150, 16, v193
	v_and_b32_e32 v151, 0xffff0000, v193
	v_lshlrev_b32_e32 v152, 16, v197
	v_and_b32_e32 v153, 0xffff0000, v197
	v_pk_fma_f32 v[42:43], v[42:43], v[150:151], v[152:153]
	v_cvt_pk_bf16_f32 v190, v44, v45
	v_cvt_pk_bf16_f32 v191, v46, v47
	v_cvt_pk_bf16_f32 v192, v40, v41
	v_cvt_pk_bf16_f32 v193, v42, v43
	global_store_dwordx4 v143, v[190:193], s[8:9]
	s_waitcnt vmcnt(14)
	v_lshlrev_b32_e32 v150, 16, v198
	v_and_b32_e32 v151, 0xffff0000, v198
	v_lshlrev_b32_e32 v152, 16, v202
	v_and_b32_e32 v153, 0xffff0000, v202
	v_pk_fma_f32 v[36:37], v[36:37], v[150:151], v[152:153]
	v_lshlrev_b32_e32 v150, 16, v199
	v_and_b32_e32 v151, 0xffff0000, v199
	v_lshlrev_b32_e32 v152, 16, v203
	v_and_b32_e32 v153, 0xffff0000, v203
	v_pk_fma_f32 v[38:39], v[38:39], v[150:151], v[152:153]
	v_lshlrev_b32_e32 v150, 16, v200
	v_and_b32_e32 v151, 0xffff0000, v200
	v_lshlrev_b32_e32 v152, 16, v204
	v_and_b32_e32 v153, 0xffff0000, v204
	v_pk_fma_f32 v[32:33], v[32:33], v[150:151], v[152:153]
	v_lshlrev_b32_e32 v150, 16, v201
	v_and_b32_e32 v151, 0xffff0000, v201
	v_lshlrev_b32_e32 v152, 16, v205
	v_and_b32_e32 v153, 0xffff0000, v205
	v_pk_fma_f32 v[34:35], v[34:35], v[150:151], v[152:153]
	v_cvt_pk_bf16_f32 v198, v36, v37
	v_cvt_pk_bf16_f32 v199, v38, v39
	v_cvt_pk_bf16_f32 v200, v32, v33
	v_cvt_pk_bf16_f32 v201, v34, v35
	global_store_dwordx4 v143, v[198:201], s[8:9] offset:256
	s_waitcnt vmcnt(12)
	v_lshlrev_b32_e32 v150, 16, v228
	v_and_b32_e32 v151, 0xffff0000, v228
	v_lshlrev_b32_e32 v152, 16, v232
	v_and_b32_e32 v153, 0xffff0000, v232
	v_pk_fma_f32 v[28:29], v[28:29], v[150:151], v[152:153]
	v_lshlrev_b32_e32 v150, 16, v229
	v_and_b32_e32 v151, 0xffff0000, v229
	v_lshlrev_b32_e32 v152, 16, v233
	v_and_b32_e32 v153, 0xffff0000, v233
	v_pk_fma_f32 v[30:31], v[30:31], v[150:151], v[152:153]
	v_lshlrev_b32_e32 v150, 16, v230
	v_and_b32_e32 v151, 0xffff0000, v230
	v_lshlrev_b32_e32 v152, 16, v234
	v_and_b32_e32 v153, 0xffff0000, v234
	v_pk_fma_f32 v[24:25], v[24:25], v[150:151], v[152:153]
	v_lshlrev_b32_e32 v150, 16, v231
	v_and_b32_e32 v151, 0xffff0000, v231
	v_lshlrev_b32_e32 v152, 16, v235
	v_and_b32_e32 v153, 0xffff0000, v235
	v_pk_fma_f32 v[26:27], v[26:27], v[150:151], v[152:153]
	v_cvt_pk_bf16_f32 v228, v28, v29
	v_cvt_pk_bf16_f32 v229, v30, v31
	v_cvt_pk_bf16_f32 v230, v24, v25
	v_cvt_pk_bf16_f32 v231, v26, v27
	global_store_dwordx4 v148, v[228:231], s[8:9]
	s_waitcnt vmcnt(10)
	v_lshlrev_b32_e32 v150, 16, v236
	v_and_b32_e32 v151, 0xffff0000, v236
	v_lshlrev_b32_e32 v152, 16, v156
	v_and_b32_e32 v153, 0xffff0000, v156
	v_pk_fma_f32 v[20:21], v[20:21], v[150:151], v[152:153]
	v_lshlrev_b32_e32 v150, 16, v237
	v_and_b32_e32 v151, 0xffff0000, v237
	v_lshlrev_b32_e32 v152, 16, v157
	v_and_b32_e32 v153, 0xffff0000, v157
	v_pk_fma_f32 v[22:23], v[22:23], v[150:151], v[152:153]
	v_lshlrev_b32_e32 v150, 16, v238
	v_and_b32_e32 v151, 0xffff0000, v238
	v_lshlrev_b32_e32 v152, 16, v158
	v_and_b32_e32 v153, 0xffff0000, v158
	v_pk_fma_f32 v[16:17], v[16:17], v[150:151], v[152:153]
	v_lshlrev_b32_e32 v150, 16, v239
	v_and_b32_e32 v151, 0xffff0000, v239
	v_lshlrev_b32_e32 v152, 16, v159
	v_and_b32_e32 v153, 0xffff0000, v159
	v_pk_fma_f32 v[18:19], v[18:19], v[150:151], v[152:153]
	v_cvt_pk_bf16_f32 v236, v20, v21
	v_cvt_pk_bf16_f32 v237, v22, v23
	v_cvt_pk_bf16_f32 v238, v16, v17
	v_cvt_pk_bf16_f32 v239, v18, v19
	global_store_dwordx4 v148, v[236:239], s[8:9] offset:256
	s_waitcnt vmcnt(8)
	v_lshlrev_b32_e32 v150, 16, v166
	v_and_b32_e32 v151, 0xffff0000, v166
	v_lshlrev_b32_e32 v152, 16, v170
	v_and_b32_e32 v153, 0xffff0000, v170
	v_pk_fma_f32 v[12:13], v[12:13], v[150:151], v[152:153]
	v_lshlrev_b32_e32 v150, 16, v167
	v_and_b32_e32 v151, 0xffff0000, v167
	v_lshlrev_b32_e32 v152, 16, v171
	v_and_b32_e32 v153, 0xffff0000, v171
	v_pk_fma_f32 v[14:15], v[14:15], v[150:151], v[152:153]
	v_lshlrev_b32_e32 v150, 16, v168
	v_and_b32_e32 v151, 0xffff0000, v168
	v_lshlrev_b32_e32 v152, 16, v172
	v_and_b32_e32 v153, 0xffff0000, v172
	v_pk_fma_f32 v[8:9], v[8:9], v[150:151], v[152:153]
	v_lshlrev_b32_e32 v150, 16, v169
	v_and_b32_e32 v151, 0xffff0000, v169
	v_lshlrev_b32_e32 v152, 16, v173
	v_and_b32_e32 v153, 0xffff0000, v173
	v_pk_fma_f32 v[10:11], v[10:11], v[150:151], v[152:153]
	v_cvt_pk_bf16_f32 v166, v12, v13
	v_cvt_pk_bf16_f32 v167, v14, v15
	v_cvt_pk_bf16_f32 v168, v8, v9
	v_cvt_pk_bf16_f32 v169, v10, v11
	global_store_dwordx4 v149, v[166:169], s[8:9]
	s_waitcnt vmcnt(6)
	v_lshlrev_b32_e32 v150, 16, v174
	v_and_b32_e32 v151, 0xffff0000, v174
	v_lshlrev_b32_e32 v152, 16, v178
	v_and_b32_e32 v153, 0xffff0000, v178
	v_pk_fma_f32 v[4:5], v[4:5], v[150:151], v[152:153]
	v_lshlrev_b32_e32 v150, 16, v175
	v_and_b32_e32 v151, 0xffff0000, v175
	v_lshlrev_b32_e32 v152, 16, v179
	v_and_b32_e32 v153, 0xffff0000, v179
	v_pk_fma_f32 v[6:7], v[6:7], v[150:151], v[152:153]
	v_lshlrev_b32_e32 v150, 16, v176
	v_and_b32_e32 v151, 0xffff0000, v176
	v_lshlrev_b32_e32 v152, 16, v180
	v_and_b32_e32 v153, 0xffff0000, v180
	v_pk_fma_f32 v[0:1], v[0:1], v[150:151], v[152:153]
	v_lshlrev_b32_e32 v150, 16, v177
	v_and_b32_e32 v151, 0xffff0000, v177
	v_lshlrev_b32_e32 v152, 16, v181
	v_and_b32_e32 v153, 0xffff0000, v181
	v_pk_fma_f32 v[2:3], v[2:3], v[150:151], v[152:153]
	v_cvt_pk_bf16_f32 v174, v4, v5
	v_cvt_pk_bf16_f32 v175, v6, v7
	v_cvt_pk_bf16_f32 v176, v0, v1
	v_cvt_pk_bf16_f32 v177, v2, v3
	global_store_dwordx4 v149, v[174:177], s[8:9] offset:256
	s_mov_b64 s[20:21], -1
	s_cbranch_vccnz .LBB0_159
	s_and_b64 vcc, exec, s[4:5]
	s_cbranch_vccnz .LBB0_158
	s_barrier
	s_branch .LBB0_158
